# adds: nt cache policy on the once-read GU row loads of the conv+SiLU phase (P8)
# speedup vs baseline: 1.0046x; 1.0024x over previous
; __global__ void __launch_bounds__(NTHR) fwd(Args args) {
;     ...
;         for (long it = gt; it < 256L * NV; it += NGT) {
;             const int strip = (int)(it / NV), cv = (int)(it % NV), c = cv * 8, m0 = strip * 32;
;             float wg[3][8], wu[3][8];
; #pragma unroll
;             for (int j = 0; j < 3; ++j) { const f32x4 a0 = *(const f32x4*)(args.ffn_conv + (size_t)j * FF2 + c), a1 = *(const f32x4*)(args.ffn_conv + (size_t)j * FF2 + c + 4),
;                                                       b0 = *(const f32x4*)(args.ffn_conv + (size_t)j * FF2 + FF + c), b1 = *(const f32x4*)(args.ffn_conv + (size_t)j * FF2 + FF + c + 4);
; #pragma unroll
;                 for (int e = 0; e < 4; ++e) { wg[j][e] = a0[e]; wg[j][4 + e] = a1[e]; wu[j][e] = b0[e]; wu[j][4 + e] = b1[e]; } }
;             const v4u zero = {0u, 0u, 0u, 0u};
;             v4u pg_ = zero, pu_ = zero;
;             if ((m0 & (SEQ - 1)) != 0) { pg_ = *(const v4u*)(GU + (size_t)(m0 - 1) * FF2 + c); pu_ = *(const v4u*)(GU + (size_t)(m0 - 1) * FF2 + FF + c); }
;             v4u cg_ = *(const v4u*)(GU + (size_t)m0 * FF2 + c), cu_ = *(const v4u*)(GU + (size_t)m0 * FF2 + FF + c);
;             for (int r = 0; r < 32; ++r) {
;                 const int m = m0 + r; v4u ng_ = zero, nu_ = zero;
;                 if ((m & (SEQ - 1)) != SEQ - 1) { ng_ = *(const v4u*)(GU + (size_t)(m + 1) * FF2 + c); nu_ = *(const v4u*)(GU + (size_t)(m + 1) * FF2 + FF + c); }
.LBB0_889:
	v_mul_hi_u32 v2, v142, s33
	v_mov_b32_e32 v3, v0
	v_mad_u64_u32 v[2:3], s[40:41], v143, s33, v[2:3]
	v_mov_b32_e32 v4, v3
	v_mov_b32_e32 v3, v0
	v_mad_u64_u32 v[2:3], s[40:41], v142, s34, v[2:3]
	v_mov_b32_e32 v5, v0
	v_mov_b32_e32 v2, v3
	v_mov_b32_e32 v3, v0
	v_lshl_add_u64 v[2:3], v[4:5], 0, v[2:3]
	v_mad_u64_u32 v[2:3], s[40:41], v143, s34, v[2:3]
	v_ashrrev_i32_e32 v1, 31, v143
	v_mad_u64_u32 v[2:3], s[40:41], v1, s33, v[2:3]
	v_mul_lo_u32 v4, v1, s34
	v_mul_lo_u32 v1, v1, s33
	v_add3_u32 v3, v1, v3, v4
	v_ashrrev_i64 v[4:5], 4, v[2:3]
	v_lshrrev_b32_e32 v2, 31, v3
	v_mov_b32_e32 v3, v0
	v_lshl_add_u64 v[2:3], v[4:5], 0, v[2:3]
	v_mul_lo_u32 v1, v2, s35
	v_sub_u32_e32 v1, v142, v1
	v_lshlrev_b32_e32 v76, 3, v1
	v_ashrrev_i32_e32 v77, 31, v76
	v_readlane_b32 s44, v253, 6
	v_lshlrev_b64 v[44:45], 2, v[76:77]
	v_readlane_b32 s50, v253, 12
	v_readlane_b32 s51, v253, 13
	v_lshl_add_u64 v[16:17], s[12:13], 0, v[44:45]
	v_lshl_add_u64 v[24:25], s[14:15], 0, v[44:45]
	v_lshl_add_u64 v[8:9], s[50:51], 0, v[44:45]
	v_lshl_add_u64 v[32:33], s[16:17], 0, v[44:45]
	v_lshl_add_u64 v[40:41], s[18:19], 0, v[44:45]
	v_lshl_add_u64 v[48:49], s[20:21], 0, v[44:45]
	global_load_dwordx4 v[4:7], v[8:9], off offset:16
	s_nop 0
	global_load_dwordx4 v[8:11], v[8:9], off
	s_nop 0
	global_load_dwordx4 v[12:15], v[16:17], off offset:16
	s_nop 0
	global_load_dwordx4 v[16:19], v[16:17], off
	s_nop 0
	global_load_dwordx4 v[20:23], v[24:25], off offset:16
	s_nop 0
	global_load_dwordx4 v[24:27], v[24:25], off
	s_nop 0
	global_load_dwordx4 v[28:31], v[32:33], off offset:16
	s_nop 0
	global_load_dwordx4 v[32:35], v[32:33], off
	s_nop 0
	global_load_dwordx4 v[36:39], v[40:41], off offset:16
	s_nop 0
	global_load_dwordx4 v[40:43], v[40:41], off
	s_nop 0
	global_load_dwordx4 v[44:47], v[48:49], off offset:16
	s_nop 0
	global_load_dwordx4 v[48:51], v[48:49], off
	v_lshlrev_b32_e32 v68, 5, v2
	v_and_b32_e32 v69, 0x7f, v2
	v_mov_b32_e32 v2, v0
	v_mov_b32_e32 v3, v0
	v_mov_b32_e32 v1, v0
	v_mov_b64_e32 v[62:63], v[2:3]
	v_mov_b64_e32 v[66:67], v[2:3]
	v_cmp_ne_u32_e32 vcc, 0, v69
	v_mov_b64_e32 v[60:61], v[0:1]
	v_mov_b64_e32 v[64:65], v[0:1]
	v_readlane_b32 s45, v253, 7
	v_readlane_b32 s46, v253, 8
	v_readlane_b32 s47, v253, 9
	v_readlane_b32 s48, v253, 10
	v_readlane_b32 s49, v253, 11
	v_readlane_b32 s52, v253, 14
	v_readlane_b32 s53, v253, 15
	v_readlane_b32 s54, v253, 16
	v_readlane_b32 s55, v253, 17
	v_readlane_b32 s56, v253, 18
	v_readlane_b32 s57, v253, 19
	v_readlane_b32 s58, v253, 20
	v_readlane_b32 s59, v253, 21
	s_and_saveexec_b64 s[40:41], vcc
	s_cbranch_execz .LBB0_891
	v_add_u32_e32 v1, -1, v68
	v_mov_b64_e32 v[2:3], s[2:3]
	v_mad_i64_i32 v[2:3], s[44:45], v1, s42, v[2:3]
	v_lshl_add_u64 v[2:3], v[76:77], 1, v[2:3]
	v_add_co_u32_e32 v52, vcc, 0x5000, v2
	s_nop 1
	v_addc_co_u32_e32 v53, vcc, 0, v3, vcc
	global_load_dwordx4 v[64:67], v[2:3], off nt
	global_load_dwordx4 v[60:63], v[52:53], off offset:1536 nt
.LBB0_891:
	s_or_b64 exec, exec, s[40:41]
	v_mov_b64_e32 v[2:3], s[2:3]
	v_mad_i64_i32 v[2:3], s[40:41], v68, s42, v[2:3]
	v_lshlrev_b64 v[70:71], 1, v[76:77]
	v_lshl_add_u64 v[2:3], v[2:3], 0, v[70:71]
	v_add_co_u32_e32 v56, vcc, 0x5000, v2
	v_lshlrev_b32_e32 v1, 5, v69
	s_nop 0
	v_addc_co_u32_e32 v57, vcc, 0, v3, vcc
	global_load_dwordx4 v[52:55], v[2:3], off nt
	s_nop 0
	global_load_dwordx4 v[56:59], v[56:57], off offset:1536 nt
	v_mad_i64_i32 v[2:3], s[40:41], v68, s43, v[70:71]
	s_mov_b32 s44, 0
	v_lshl_add_u64 v[78:79], s[0:1], 0, v[2:3]
	v_add_u32_e32 v80, 1, v68
	v_xor_b32_e32 v81, 0xfff, v1
	v_mov_b32_e32 v2, v0
	v_mov_b32_e32 v3, v0
	v_mov_b32_e32 v1, v0
	v_mov_b64_e32 v[70:71], v[2:3]
	v_mov_b64_e32 v[74:75], v[2:3]
	v_cmp_ne_u32_e32 vcc, s44, v81
	v_mov_b64_e32 v[68:69], v[0:1]
	v_mov_b64_e32 v[72:73], v[0:1]
	s_and_saveexec_b64 s[40:41], vcc
	v_add_u32_e32 v1, s44, v80
	v_mov_b64_e32 v[2:3], s[2:3]
	v_mad_i64_i32 v[2:3], s[46:47], v1, s42, v[2:3]
	v_lshl_add_u64 v[2:3], v[76:77], 1, v[2:3]
	v_add_co_u32_e32 v72, vcc, 0x5000, v2
	s_nop 1
	v_addc_co_u32_e32 v73, vcc, 0, v3, vcc
	global_load_dwordx4 v[68:71], v[2:3], off nt
	s_nop 0
	global_load_dwordx4 v[72:75], v[72:73], off offset:1536 nt
	s_or_b64 exec, exec, s[40:41]
.Lp8_rows:
	v_mov_b32_e32 v2, v0
	v_mov_b32_e32 v3, v0
	v_mov_b32_e32 v1, v0
	v_mov_b64_e32 v[90:91], v[2:3]
	v_mov_b64_e32 v[94:95], v[2:3]
	s_add_i32 s46, s44, 1
	v_cmp_ne_u32_e32 vcc, s46, v81
	v_mov_b64_e32 v[88:89], v[0:1]
	v_mov_b64_e32 v[92:93], v[0:1]
	s_and_saveexec_b64 s[40:41], vcc
	v_add_u32_e32 v1, s46, v80
	v_mov_b64_e32 v[2:3], s[2:3]
	v_mad_i64_i32 v[2:3], s[46:47], v1, s42, v[2:3]
	v_lshl_add_u64 v[2:3], v[76:77], 1, v[2:3]
	v_add_co_u32_e32 v92, vcc, 0x5000, v2
	s_nop 1
	v_addc_co_u32_e32 v93, vcc, 0, v3, vcc
	global_load_dwordx4 v[88:91], v[2:3], off nt
	s_nop 0
	global_load_dwordx4 v[92:95], v[92:93], off offset:1536 nt
	s_or_b64 exec, exec, s[40:41]
	s_waitcnt vmcnt(4)
	v_lshlrev_b32_e32 v82, 16, v52
	v_and_b32_e32 v83, 0xffff0000, v52
	v_lshlrev_b32_e32 v2, 16, v64
	v_and_b32_e32 v3, 0xffff0000, v64
	v_pk_mul_f32 v[82:83], v[24:25], v[82:83]
	s_waitcnt vmcnt(2)
; __device__ __forceinline__ unsigned pk2(float lo, float hi) { const f32x2 v = {lo, hi}; const hwbf16x2 r = __builtin_convertvector(v, hwbf16x2); return __builtin_bit_cast(unsigned, r); }
; __device__ __forceinline__ float bf_lo(unsigned v) { return __uint_as_float(v << 16); }
; __device__ __forceinline__ float bf_hi(unsigned v) { return __uint_as_float(v & 0xffff0000u); }
; __device__ __forceinline__ float silu_f(float x) { return x * __builtin_amdgcn_rcpf(1.0f + __expf(-x)); }
; __global__ void __launch_bounds__(NTHR) fwd(Args args) {
;     ...
;             for (int r = 0; r < 32; ++r) {
;                 const int m = m0 + r; v4u ng_ = zero, nu_ = zero;
;                 if ((m & (SEQ - 1)) != SEQ - 1) { ng_ = *(const v4u*)(GU + (size_t)(m + 1) * FF2 + c); nu_ = *(const v4u*)(GU + (size_t)(m + 1) * FF2 + FF + c); }
;                 v4u ov;
; #pragma unroll
;                 for (int e = 0; e < 4; ++e) {
;                     const float g0 = wg[0][2 * e] * bf_lo(pg_[e]) + wg[1][2 * e] * bf_lo(cg_[e]) + wg[2][2 * e] * bf_lo(ng_[e]);
;                     const float g1 = wg[0][2 * e + 1] * bf_hi(pg_[e]) + wg[1][2 * e + 1] * bf_hi(cg_[e]) + wg[2][2 * e + 1] * bf_hi(ng_[e]);
;                     const float u0 = wu[0][2 * e] * bf_lo(pu_[e]) + wu[1][2 * e] * bf_lo(cu_[e]) + wu[2][2 * e] * bf_lo(nu_[e]);
;                     const float u1 = wu[0][2 * e + 1] * bf_hi(pu_[e]) + wu[1][2 * e + 1] * bf_hi(cu_[e]) + wu[2][2 * e + 1] * bf_hi(nu_[e]);
;                     ov[e] = pk2(silu_f(g0) * u0, silu_f(g1) * u1);
;                 }
;                 *(v4u*)(ACT + (size_t)m * FF + c) = ov;
;                 pg_ = cg_; pu_ = cu_; cg_ = ng_; cu_ = nu_;
	v_lshlrev_b32_e32 v84, 16, v56
	v_pk_fma_f32 v[2:3], v[8:9], v[2:3], v[82:83]
	v_lshlrev_b32_e32 v82, 16, v68
	v_and_b32_e32 v83, 0xffff0000, v68
	v_pk_fma_f32 v[2:3], v[40:41], v[82:83], v[2:3]
	v_lshlrev_b32_e32 v82, 16, v60
	v_mul_f32_e32 v1, 0xbfb8aa3b, v2
	v_and_b32_e32 v83, 0xffff0000, v60
	v_exp_f32_e32 v1, v1
	v_mul_f32_e32 v60, 0xbfb8aa3b, v3
	v_exp_f32_e32 v60, v60
	v_and_b32_e32 v85, 0xffff0000, v56
	v_pk_mul_f32 v[84:85], v[32:33], v[84:85]
	v_add_f32_e32 v1, 1.0, v1
	v_pk_fma_f32 v[82:83], v[16:17], v[82:83], v[84:85]
	v_rcp_f32_e32 v84, v1
	v_add_f32_e32 v1, 1.0, v60
	v_rcp_f32_e32 v85, v1
	v_lshlrev_b32_e32 v86, 16, v72
	v_and_b32_e32 v87, 0xffff0000, v72
	v_pk_fma_f32 v[82:83], v[48:49], v[86:87], v[82:83]
	v_pk_mul_f32 v[2:3], v[2:3], v[84:85]
	v_lshlrev_b32_e32 v64, 16, v53
	v_pk_mul_f32 v[2:3], v[2:3], v[82:83]
	v_lshlrev_b32_e32 v82, 16, v57
	v_cvt_pk_bf16_f32 v60, v2, v3
	v_lshlrev_b32_e32 v2, 16, v65
	v_and_b32_e32 v3, 0xffff0000, v65
	v_and_b32_e32 v65, 0xffff0000, v53
	v_pk_mul_f32 v[64:65], v[26:27], v[64:65]
	v_and_b32_e32 v83, 0xffff0000, v57
	v_pk_fma_f32 v[2:3], v[10:11], v[2:3], v[64:65]
	v_lshlrev_b32_e32 v64, 16, v69
	v_and_b32_e32 v65, 0xffff0000, v69
	v_pk_fma_f32 v[2:3], v[42:43], v[64:65], v[2:3]
	v_lshlrev_b32_e32 v64, 16, v61
	v_mul_f32_e32 v1, 0xbfb8aa3b, v2
	v_and_b32_e32 v65, 0xffff0000, v61
	v_exp_f32_e32 v1, v1
	v_mul_f32_e32 v61, 0xbfb8aa3b, v3
	v_exp_f32_e32 v61, v61
	v_pk_mul_f32 v[82:83], v[34:35], v[82:83]
	v_add_f32_e32 v1, 1.0, v1
	v_pk_fma_f32 v[64:65], v[18:19], v[64:65], v[82:83]
	v_rcp_f32_e32 v82, v1
	v_add_f32_e32 v1, 1.0, v61
	v_rcp_f32_e32 v83, v1
	v_lshlrev_b32_e32 v84, 16, v73
	v_and_b32_e32 v85, 0xffff0000, v73
	v_pk_fma_f32 v[64:65], v[50:51], v[84:85], v[64:65]
	v_pk_mul_f32 v[2:3], v[2:3], v[82:83]
	v_lshlrev_b32_e32 v82, 16, v58
	v_pk_mul_f32 v[2:3], v[2:3], v[64:65]
	v_lshlrev_b32_e32 v64, 16, v54
	v_and_b32_e32 v65, 0xffff0000, v54
	v_cvt_pk_bf16_f32 v61, v2, v3
	v_lshlrev_b32_e32 v2, 16, v66
	v_and_b32_e32 v3, 0xffff0000, v66
	v_pk_mul_f32 v[64:65], v[20:21], v[64:65]
	v_and_b32_e32 v83, 0xffff0000, v58
	v_pk_fma_f32 v[2:3], v[4:5], v[2:3], v[64:65]
	v_lshlrev_b32_e32 v64, 16, v70
	v_and_b32_e32 v65, 0xffff0000, v70
	v_pk_fma_f32 v[2:3], v[36:37], v[64:65], v[2:3]
	v_lshlrev_b32_e32 v64, 16, v62
	v_mul_f32_e32 v1, 0xbfb8aa3b, v2
	v_and_b32_e32 v65, 0xffff0000, v62
	v_exp_f32_e32 v1, v1
	v_mul_f32_e32 v62, 0xbfb8aa3b, v3
	v_exp_f32_e32 v62, v62
	v_pk_mul_f32 v[82:83], v[28:29], v[82:83]
	v_add_f32_e32 v1, 1.0, v1
	v_pk_fma_f32 v[64:65], v[12:13], v[64:65], v[82:83]
	v_rcp_f32_e32 v82, v1
	v_add_f32_e32 v1, 1.0, v62
	v_rcp_f32_e32 v83, v1
	v_lshlrev_b32_e32 v84, 16, v74
	v_and_b32_e32 v85, 0xffff0000, v74
	v_pk_fma_f32 v[64:65], v[44:45], v[84:85], v[64:65]
	v_pk_mul_f32 v[2:3], v[2:3], v[82:83]
	v_lshlrev_b32_e32 v66, 16, v59
	v_pk_mul_f32 v[2:3], v[2:3], v[64:65]
	v_lshlrev_b32_e32 v64, 16, v55
	v_and_b32_e32 v65, 0xffff0000, v55
	v_cvt_pk_bf16_f32 v62, v2, v3
	v_lshlrev_b32_e32 v2, 16, v67
	v_and_b32_e32 v3, 0xffff0000, v67
	v_pk_mul_f32 v[64:65], v[22:23], v[64:65]
	v_and_b32_e32 v67, 0xffff0000, v59
	v_pk_fma_f32 v[2:3], v[6:7], v[2:3], v[64:65]
	v_lshlrev_b32_e32 v64, 16, v71
	v_and_b32_e32 v65, 0xffff0000, v71
	v_pk_fma_f32 v[2:3], v[38:39], v[64:65], v[2:3]
	v_lshlrev_b32_e32 v64, 16, v63
	v_mul_f32_e32 v1, 0xbfb8aa3b, v2
	v_and_b32_e32 v65, 0xffff0000, v63
	v_exp_f32_e32 v1, v1
	v_mul_f32_e32 v63, 0xbfb8aa3b, v3
	v_exp_f32_e32 v63, v63
	v_pk_mul_f32 v[66:67], v[30:31], v[66:67]
	v_add_f32_e32 v1, 1.0, v1
	v_pk_fma_f32 v[64:65], v[14:15], v[64:65], v[66:67]
	v_rcp_f32_e32 v66, v1
	v_add_f32_e32 v1, 1.0, v63
	v_rcp_f32_e32 v67, v1
	v_lshlrev_b32_e32 v82, 16, v75
	v_and_b32_e32 v83, 0xffff0000, v75
	v_pk_fma_f32 v[64:65], v[46:47], v[82:83], v[64:65]
	v_pk_mul_f32 v[2:3], v[2:3], v[66:67]
	s_add_i32 s44, s44, 1
	v_pk_mul_f32 v[2:3], v[2:3], v[64:65]
	v_mov_b64_e32 v[66:67], v[54:55]
	v_cvt_pk_bf16_f32 v63, v2, v3
	global_store_dwordx4 v[78:79], v[60:63], off
	v_mov_b64_e32 v[64:65], v[52:53]
	v_mov_b64_e32 v[52:53], v[68:69]
	v_mov_b64_e32 v[62:63], v[58:59]
	v_mov_b64_e32 v[60:61], v[56:57]
	v_mov_b64_e32 v[56:57], v[72:73]
	v_lshl_add_u64 v[78:79], v[78:79], 0, s[36:37]
	v_mov_b64_e32 v[54:55], v[70:71]
	v_mov_b64_e32 v[58:59], v[74:75]
	v_mov_b32_e32 v2, v0
	v_mov_b32_e32 v3, v0
	v_mov_b32_e32 v1, v0
	v_mov_b64_e32 v[70:71], v[2:3]
	v_mov_b64_e32 v[74:75], v[2:3]
	s_add_i32 s46, s44, 1
	v_cmp_ne_u32_e32 vcc, s46, v81
	v_mov_b64_e32 v[68:69], v[0:1]
	v_mov_b64_e32 v[72:73], v[0:1]
	s_and_saveexec_b64 s[40:41], vcc
	v_add_u32_e32 v1, s46, v80
	v_mov_b64_e32 v[2:3], s[2:3]
	v_mad_i64_i32 v[2:3], s[46:47], v1, s42, v[2:3]
	v_lshl_add_u64 v[2:3], v[76:77], 1, v[2:3]
	v_add_co_u32_e32 v72, vcc, 0x5000, v2
	s_nop 1
	v_addc_co_u32_e32 v73, vcc, 0, v3, vcc
	global_load_dwordx4 v[68:71], v[2:3], off nt
	s_nop 0
	global_load_dwordx4 v[72:75], v[72:73], off offset:1536 nt
	s_or_b64 exec, exec, s[40:41]
	s_waitcnt vmcnt(4)
; __device__ __forceinline__ unsigned pk2(float lo, float hi) { const f32x2 v = {lo, hi}; const hwbf16x2 r = __builtin_convertvector(v, hwbf16x2); return __builtin_bit_cast(unsigned, r); }
; __device__ __forceinline__ float bf_lo(unsigned v) { return __uint_as_float(v << 16); }
; __device__ __forceinline__ float bf_hi(unsigned v) { return __uint_as_float(v & 0xffff0000u); }
; __device__ __forceinline__ float silu_f(float x) { return x * __builtin_amdgcn_rcpf(1.0f + __expf(-x)); }
; __global__ void __launch_bounds__(NTHR) fwd(Args args) {
;     ...
;             for (int r = 0; r < 32; ++r) {
;                 const int m = m0 + r; v4u ng_ = zero, nu_ = zero;
;                 if ((m & (SEQ - 1)) != SEQ - 1) { ng_ = *(const v4u*)(GU + (size_t)(m + 1) * FF2 + c); nu_ = *(const v4u*)(GU + (size_t)(m + 1) * FF2 + FF + c); }
;                 v4u ov;
; #pragma unroll
;                 for (int e = 0; e < 4; ++e) {
;                     const float g0 = wg[0][2 * e] * bf_lo(pg_[e]) + wg[1][2 * e] * bf_lo(cg_[e]) + wg[2][2 * e] * bf_lo(ng_[e]);
;                     const float g1 = wg[0][2 * e + 1] * bf_hi(pg_[e]) + wg[1][2 * e + 1] * bf_hi(cg_[e]) + wg[2][2 * e + 1] * bf_hi(ng_[e]);
;                     const float u0 = wu[0][2 * e] * bf_lo(pu_[e]) + wu[1][2 * e] * bf_lo(cu_[e]) + wu[2][2 * e] * bf_lo(nu_[e]);
;                     const float u1 = wu[0][2 * e + 1] * bf_hi(pu_[e]) + wu[1][2 * e + 1] * bf_hi(cu_[e]) + wu[2][2 * e + 1] * bf_hi(nu_[e]);
;                     ov[e] = pk2(silu_f(g0) * u0, silu_f(g1) * u1);
;                 }
;                 *(v4u*)(ACT + (size_t)m * FF + c) = ov;
;                 pg_ = cg_; pu_ = cu_; cg_ = ng_; cu_ = nu_;
;             }
	v_lshlrev_b32_e32 v82, 16, v52
	v_and_b32_e32 v83, 0xffff0000, v52
	v_lshlrev_b32_e32 v2, 16, v64
	v_and_b32_e32 v3, 0xffff0000, v64
	v_pk_mul_f32 v[82:83], v[24:25], v[82:83]
	s_waitcnt vmcnt(2)
	v_lshlrev_b32_e32 v84, 16, v56
	v_pk_fma_f32 v[2:3], v[8:9], v[2:3], v[82:83]
	v_lshlrev_b32_e32 v82, 16, v88
	v_and_b32_e32 v83, 0xffff0000, v88
	v_pk_fma_f32 v[2:3], v[40:41], v[82:83], v[2:3]
	v_lshlrev_b32_e32 v82, 16, v60
	v_mul_f32_e32 v1, 0xbfb8aa3b, v2
	v_and_b32_e32 v83, 0xffff0000, v60
	v_exp_f32_e32 v1, v1
	v_mul_f32_e32 v60, 0xbfb8aa3b, v3
	v_exp_f32_e32 v60, v60
	v_and_b32_e32 v85, 0xffff0000, v56
	v_pk_mul_f32 v[84:85], v[32:33], v[84:85]
	v_add_f32_e32 v1, 1.0, v1
	v_pk_fma_f32 v[82:83], v[16:17], v[82:83], v[84:85]
	v_rcp_f32_e32 v84, v1
	v_add_f32_e32 v1, 1.0, v60
	v_rcp_f32_e32 v85, v1
	v_lshlrev_b32_e32 v86, 16, v92
	v_and_b32_e32 v87, 0xffff0000, v92
	v_pk_fma_f32 v[82:83], v[48:49], v[86:87], v[82:83]
	v_pk_mul_f32 v[2:3], v[2:3], v[84:85]
	v_lshlrev_b32_e32 v64, 16, v53
	v_pk_mul_f32 v[2:3], v[2:3], v[82:83]
	v_lshlrev_b32_e32 v82, 16, v57
	v_cvt_pk_bf16_f32 v60, v2, v3
	v_lshlrev_b32_e32 v2, 16, v65
	v_and_b32_e32 v3, 0xffff0000, v65
	v_and_b32_e32 v65, 0xffff0000, v53
	v_pk_mul_f32 v[64:65], v[26:27], v[64:65]
	v_and_b32_e32 v83, 0xffff0000, v57
	v_pk_fma_f32 v[2:3], v[10:11], v[2:3], v[64:65]
	v_lshlrev_b32_e32 v64, 16, v89
	v_and_b32_e32 v65, 0xffff0000, v89
	v_pk_fma_f32 v[2:3], v[42:43], v[64:65], v[2:3]
	v_lshlrev_b32_e32 v64, 16, v61
	v_mul_f32_e32 v1, 0xbfb8aa3b, v2
	v_and_b32_e32 v65, 0xffff0000, v61
	v_exp_f32_e32 v1, v1
	v_mul_f32_e32 v61, 0xbfb8aa3b, v3
	v_exp_f32_e32 v61, v61
	v_pk_mul_f32 v[82:83], v[34:35], v[82:83]
	v_add_f32_e32 v1, 1.0, v1
	v_pk_fma_f32 v[64:65], v[18:19], v[64:65], v[82:83]
	v_rcp_f32_e32 v82, v1
	v_add_f32_e32 v1, 1.0, v61
	v_rcp_f32_e32 v83, v1
	v_lshlrev_b32_e32 v84, 16, v93
	v_and_b32_e32 v85, 0xffff0000, v93
	v_pk_fma_f32 v[64:65], v[50:51], v[84:85], v[64:65]
	v_pk_mul_f32 v[2:3], v[2:3], v[82:83]
	v_lshlrev_b32_e32 v82, 16, v58
	v_pk_mul_f32 v[2:3], v[2:3], v[64:65]
	v_lshlrev_b32_e32 v64, 16, v54
	v_and_b32_e32 v65, 0xffff0000, v54
	v_cvt_pk_bf16_f32 v61, v2, v3
	v_lshlrev_b32_e32 v2, 16, v66
	v_and_b32_e32 v3, 0xffff0000, v66
	v_pk_mul_f32 v[64:65], v[20:21], v[64:65]
	v_and_b32_e32 v83, 0xffff0000, v58
	v_pk_fma_f32 v[2:3], v[4:5], v[2:3], v[64:65]
	v_lshlrev_b32_e32 v64, 16, v90
	v_and_b32_e32 v65, 0xffff0000, v90
	v_pk_fma_f32 v[2:3], v[36:37], v[64:65], v[2:3]
	v_lshlrev_b32_e32 v64, 16, v62
	v_mul_f32_e32 v1, 0xbfb8aa3b, v2
	v_and_b32_e32 v65, 0xffff0000, v62
	v_exp_f32_e32 v1, v1
	v_mul_f32_e32 v62, 0xbfb8aa3b, v3
	v_exp_f32_e32 v62, v62
	v_pk_mul_f32 v[82:83], v[28:29], v[82:83]
	v_add_f32_e32 v1, 1.0, v1
	v_pk_fma_f32 v[64:65], v[12:13], v[64:65], v[82:83]
	v_rcp_f32_e32 v82, v1
	v_add_f32_e32 v1, 1.0, v62
	v_rcp_f32_e32 v83, v1
	v_lshlrev_b32_e32 v84, 16, v94
	v_and_b32_e32 v85, 0xffff0000, v94
	v_pk_fma_f32 v[64:65], v[44:45], v[84:85], v[64:65]
	v_pk_mul_f32 v[2:3], v[2:3], v[82:83]
	v_lshlrev_b32_e32 v66, 16, v59
	v_pk_mul_f32 v[2:3], v[2:3], v[64:65]
	v_lshlrev_b32_e32 v64, 16, v55
	v_and_b32_e32 v65, 0xffff0000, v55
	v_cvt_pk_bf16_f32 v62, v2, v3
	v_lshlrev_b32_e32 v2, 16, v67
	v_and_b32_e32 v3, 0xffff0000, v67
	v_pk_mul_f32 v[64:65], v[22:23], v[64:65]
	v_and_b32_e32 v67, 0xffff0000, v59
	v_pk_fma_f32 v[2:3], v[6:7], v[2:3], v[64:65]
	v_lshlrev_b32_e32 v64, 16, v91
	v_and_b32_e32 v65, 0xffff0000, v91
	v_pk_fma_f32 v[2:3], v[38:39], v[64:65], v[2:3]
	v_lshlrev_b32_e32 v64, 16, v63
	v_mul_f32_e32 v1, 0xbfb8aa3b, v2
	v_and_b32_e32 v65, 0xffff0000, v63
	v_exp_f32_e32 v1, v1
	v_mul_f32_e32 v63, 0xbfb8aa3b, v3
	v_exp_f32_e32 v63, v63
	v_pk_mul_f32 v[66:67], v[30:31], v[66:67]
	v_add_f32_e32 v1, 1.0, v1
	v_pk_fma_f32 v[64:65], v[14:15], v[64:65], v[66:67]
	v_rcp_f32_e32 v66, v1
	v_add_f32_e32 v1, 1.0, v63
	v_rcp_f32_e32 v67, v1
	v_lshlrev_b32_e32 v82, 16, v95
	v_and_b32_e32 v83, 0xffff0000, v95
	v_pk_fma_f32 v[64:65], v[46:47], v[82:83], v[64:65]
	v_pk_mul_f32 v[2:3], v[2:3], v[66:67]
	s_add_i32 s44, s44, 1
	v_pk_mul_f32 v[2:3], v[2:3], v[64:65]
	v_mov_b64_e32 v[66:67], v[54:55]
	v_cvt_pk_bf16_f32 v63, v2, v3
	global_store_dwordx4 v[78:79], v[60:63], off
	v_mov_b64_e32 v[64:65], v[52:53]
	v_mov_b64_e32 v[52:53], v[88:89]
	v_mov_b64_e32 v[62:63], v[58:59]
	v_mov_b64_e32 v[60:61], v[56:57]
	v_mov_b64_e32 v[56:57], v[92:93]
	v_lshl_add_u64 v[78:79], v[78:79], 0, s[36:37]
	v_mov_b64_e32 v[54:55], v[90:91]
	v_mov_b64_e32 v[58:59], v[94:95]
	s_cmp_eq_u32 s44, 32
	s_cbranch_scc0 .Lp8_rows
	s_waitcnt vmcnt(0)
	s_branch .LBB0_888
